# P8 HID stores with sc1 nt cache policy
# speedup vs baseline: 1.0136x; 1.0034x over previous
.LBB0_877:
	s_cmp_eq_u32 s100, 0
	s_cbranch_scc1 .Ldhs8_idle
	s_cmp_lt_i32 s61, 6
	s_cbranch_scc0 .Ldhs8_hi
	s_cmp_lt_i32 s61, 2
	s_cbranch_scc0 .Ldhs8_q1
	s_cmp_lt_i32 s61, 0
	s_cbranch_scc0 .Ldhs8_g9
	global_store_dwordx4 v255, v[226:229], s[16:17] sc1 nt
	s_branch .Ldhs8_done
.Ldhs8_g9:
	global_store_dwordx4 v255, v[230:233], s[18:19] sc1 nt
	s_branch .Ldhs8_done
.Ldhs8_q1:
	s_cmp_lt_i32 s61, 4
	s_cbranch_scc0 .Ldhs8_g11
	global_store_dwordx4 v255, v[234:237], s[16:17] offset:1024 sc1 nt
	s_branch .Ldhs8_done
.Ldhs8_g11:
	global_store_dwordx4 v255, v[238:241], s[18:19] offset:1024 sc1 nt
	s_branch .Ldhs8_done
.Ldhs8_hi:
	s_cmp_lt_i32 s61, 10
	s_cbranch_scc0 .Ldhs8_q3
	s_cmp_lt_i32 s61, 8
	s_cbranch_scc0 .Ldhs8_g13
	global_store_dwordx4 v255, v[242:245], s[16:17] offset:2048 sc1 nt
	s_branch .Ldhs8_done
.Ldhs8_g13:
	global_store_dwordx4 v255, v[246:249], s[18:19] offset:2048 sc1 nt
	s_branch .Ldhs8_done
.Ldhs8_q3:
	s_cmp_lt_i32 s61, 12
	s_cbranch_scc0 .Ldhs8_g15
	global_store_dwordx4 v255, v[250:253], s[16:17] offset:3072 sc1 nt
	s_branch .Ldhs8_done
.Ldhs8_g15:
	global_store_dwordx4 v255, v[140:143], s[18:19] offset:3072 sc1 nt
	s_branch .Ldhs8_done

.LBB0_880:
	v_lshl_add_u32 v150, s34, 8, v144
	v_lshl_or_b32 v152, s56, 8, v146
	v_ashrrev_i32_e32 v151, 31, v150
	v_max_f32_e32 v124, 0, v124
	v_max_f32_e32 v120, 0, v120
	v_max_f32_e32 v125, 0, v125
	v_max_f32_e32 v121, 0, v121
	v_max_f32_e32 v126, 0, v126
	v_max_f32_e32 v127, 0, v127
	v_ashrrev_i32_e32 v153, 31, v152
	v_lshlrev_b64 v[154:155], 6, v[150:151]
	v_pk_mul_f32 v[124:125], v[124:125], v[124:125]
	v_pk_mul_f32 v[120:121], v[120:121], v[120:121]
	v_max_f32_e32 v122, 0, v122
	v_max_f32_e32 v123, 0, v123
	v_pk_mul_f32 v[126:127], v[126:127], v[126:127]
	v_pk_mul_f32 v[156:157], v[122:123], v[122:123]
	v_cvt_pk_bf16_f32 v122, v124, v125
	v_cvt_pk_bf16_f32 v123, v126, v127
	v_cvt_pk_bf16_f32 v124, v120, v121
	v_lshl_add_u64 v[120:121], s[78:79], 0, v[154:155]
	v_and_b32_e32 v126, 0xfe0, v152
	v_and_b32_e32 v127, 31, v152
	v_lshlrev_b32_e32 v126, 16, v126
	v_lshl_or_b32 v126, v127, 1, v126
	v_add_u32_e32 v255, v154, v126
	v_mov_b32_e32 v127, 0
	v_cvt_pk_bf16_f32 v125, v156, v157
	v_lshl_add_u64 v[120:121], v[120:121], 0, v[126:127]
	v_max_f32_e32 v112, 0, v112
	v_max_f32_e32 v113, 0, v113
	global_store_dwordx4 v[120:121], v[122:125], off sc1 nt
	s_nop 1
	v_pk_mul_f32 v[122:123], v[112:113], v[112:113]
	v_max_f32_e32 v114, 0, v114
	v_max_f32_e32 v116, 0, v116
	v_max_f32_e32 v117, 0, v117
	v_max_f32_e32 v112, 0, v118
	v_max_f32_e32 v113, 0, v119
	v_max_f32_e32 v115, 0, v115
	v_pk_mul_f32 v[116:117], v[116:117], v[116:117]
	v_pk_mul_f32 v[118:119], v[112:113], v[112:113]
	v_pk_mul_f32 v[124:125], v[114:115], v[114:115]
	v_cvt_pk_bf16_f32 v112, v116, v117
	v_cvt_pk_bf16_f32 v113, v118, v119
	v_cvt_pk_bf16_f32 v114, v122, v123
	v_cvt_pk_bf16_f32 v115, v124, v125
	v_max_f32_e32 v104, 0, v104
	v_max_f32_e32 v105, 0, v105
	v_lshl_add_u64 v[200:201], v[120:121], 0, s[98:99]
	global_store_dwordx4 v[200:201], v[112:115], off sc1 nt
	s_nop 1
	v_or_b32_e32 v112, 16, v150
	v_pk_mul_f32 v[114:115], v[104:105], v[104:105]
	v_ashrrev_i32_e32 v113, 31, v112
	v_max_f32_e32 v108, 0, v108
	v_max_f32_e32 v109, 0, v109
	v_max_f32_e32 v106, 0, v106
	v_lshlrev_b64 v[112:113], 6, v[112:113]
	v_pk_mul_f32 v[108:109], v[108:109], v[108:109]
	v_max_f32_e32 v104, 0, v110
	v_max_f32_e32 v105, 0, v111
	v_max_f32_e32 v107, 0, v107
	v_pk_mul_f32 v[110:111], v[104:105], v[104:105]
	v_pk_mul_f32 v[116:117], v[106:107], v[106:107]
	v_cvt_pk_bf16_f32 v104, v108, v109
	v_lshl_add_u64 v[108:109], s[78:79], 0, v[112:113]
	v_cvt_pk_bf16_f32 v105, v110, v111
	v_cvt_pk_bf16_f32 v106, v114, v115
	v_cvt_pk_bf16_f32 v107, v116, v117
	v_lshl_add_u64 v[108:109], v[108:109], 0, v[126:127]
	v_max_f32_e32 v96, 0, v96
	v_max_f32_e32 v97, 0, v97
	global_store_dwordx4 v[108:109], v[104:107], off sc1 nt
	s_nop 1
	v_pk_mul_f32 v[104:105], v[96:97], v[96:97]
	v_max_f32_e32 v98, 0, v98
	v_max_f32_e32 v100, 0, v100
	v_max_f32_e32 v101, 0, v101
	v_max_f32_e32 v96, 0, v102
	v_max_f32_e32 v97, 0, v103
	v_max_f32_e32 v99, 0, v99
	v_pk_mul_f32 v[100:101], v[100:101], v[100:101]
	v_pk_mul_f32 v[102:103], v[96:97], v[96:97]
	v_pk_mul_f32 v[106:107], v[98:99], v[98:99]
	v_cvt_pk_bf16_f32 v96, v100, v101
	v_cvt_pk_bf16_f32 v97, v102, v103
	v_cvt_pk_bf16_f32 v98, v104, v105
	v_cvt_pk_bf16_f32 v99, v106, v107
	v_max_f32_e32 v88, 0, v88
	v_max_f32_e32 v89, 0, v89
	v_lshl_add_u64 v[202:203], v[108:109], 0, s[98:99]
	global_store_dwordx4 v[202:203], v[96:99], off sc1 nt
	s_nop 1
	v_or_b32_e32 v96, 32, v150
	v_pk_mul_f32 v[98:99], v[88:89], v[88:89]
	v_ashrrev_i32_e32 v97, 31, v96
	v_max_f32_e32 v92, 0, v92
	v_max_f32_e32 v93, 0, v93
	v_max_f32_e32 v90, 0, v90
	v_lshlrev_b64 v[96:97], 6, v[96:97]
	v_pk_mul_f32 v[92:93], v[92:93], v[92:93]
	v_max_f32_e32 v88, 0, v94
	v_max_f32_e32 v89, 0, v95
	v_max_f32_e32 v91, 0, v91
	v_pk_mul_f32 v[94:95], v[88:89], v[88:89]
	v_pk_mul_f32 v[100:101], v[90:91], v[90:91]
	v_cvt_pk_bf16_f32 v88, v92, v93
	v_lshl_add_u64 v[92:93], s[78:79], 0, v[96:97]
	v_cvt_pk_bf16_f32 v89, v94, v95
	v_cvt_pk_bf16_f32 v90, v98, v99
	v_cvt_pk_bf16_f32 v91, v100, v101
	v_lshl_add_u64 v[92:93], v[92:93], 0, v[126:127]
	v_max_f32_e32 v80, 0, v80
	v_max_f32_e32 v81, 0, v81
	global_store_dwordx4 v[92:93], v[88:91], off sc1 nt
	s_nop 1
	v_pk_mul_f32 v[88:89], v[80:81], v[80:81]
	v_max_f32_e32 v82, 0, v82
	v_max_f32_e32 v84, 0, v84
	v_max_f32_e32 v85, 0, v85
	v_max_f32_e32 v80, 0, v86
	v_max_f32_e32 v81, 0, v87
	v_max_f32_e32 v83, 0, v83
	v_pk_mul_f32 v[84:85], v[84:85], v[84:85]
	v_pk_mul_f32 v[86:87], v[80:81], v[80:81]
	v_pk_mul_f32 v[90:91], v[82:83], v[82:83]
	v_cvt_pk_bf16_f32 v80, v84, v85
	v_cvt_pk_bf16_f32 v81, v86, v87
	v_cvt_pk_bf16_f32 v82, v88, v89
	v_cvt_pk_bf16_f32 v83, v90, v91
	v_max_f32_e32 v72, 0, v72
	v_max_f32_e32 v73, 0, v73
	v_lshl_add_u64 v[204:205], v[92:93], 0, s[98:99]
	global_store_dwordx4 v[204:205], v[80:83], off sc1 nt
	s_nop 1
	v_or_b32_e32 v80, 48, v150
	v_pk_mul_f32 v[82:83], v[72:73], v[72:73]
	v_ashrrev_i32_e32 v81, 31, v80
	v_max_f32_e32 v76, 0, v76
	v_max_f32_e32 v77, 0, v77
	v_max_f32_e32 v74, 0, v74
	v_lshlrev_b64 v[80:81], 6, v[80:81]
	v_pk_mul_f32 v[76:77], v[76:77], v[76:77]
	v_max_f32_e32 v72, 0, v78
	v_max_f32_e32 v73, 0, v79
	v_max_f32_e32 v75, 0, v75
	v_pk_mul_f32 v[78:79], v[72:73], v[72:73]
	v_pk_mul_f32 v[84:85], v[74:75], v[74:75]
	v_cvt_pk_bf16_f32 v72, v76, v77
	v_lshl_add_u64 v[76:77], s[78:79], 0, v[80:81]
	v_cvt_pk_bf16_f32 v73, v78, v79
	v_cvt_pk_bf16_f32 v74, v82, v83
	v_cvt_pk_bf16_f32 v75, v84, v85
	v_lshl_add_u64 v[76:77], v[76:77], 0, v[126:127]
	v_max_f32_e32 v64, 0, v64
	v_max_f32_e32 v65, 0, v65
	global_store_dwordx4 v[76:77], v[72:75], off sc1 nt
	s_nop 1
	v_pk_mul_f32 v[72:73], v[64:65], v[64:65]
	v_max_f32_e32 v66, 0, v66
	v_max_f32_e32 v68, 0, v68
	v_max_f32_e32 v69, 0, v69
	v_max_f32_e32 v64, 0, v70
	v_max_f32_e32 v65, 0, v71
	v_max_f32_e32 v67, 0, v67
	v_pk_mul_f32 v[68:69], v[68:69], v[68:69]
	v_pk_mul_f32 v[70:71], v[64:65], v[64:65]
	v_pk_mul_f32 v[74:75], v[66:67], v[66:67]
	v_cvt_pk_bf16_f32 v64, v68, v69
	v_cvt_pk_bf16_f32 v65, v70, v71
	v_cvt_pk_bf16_f32 v66, v72, v73
	v_cvt_pk_bf16_f32 v67, v74, v75
	v_max_f32_e32 v56, 0, v56
	v_max_f32_e32 v57, 0, v57
	v_lshl_add_u64 v[206:207], v[76:77], 0, s[98:99]
	global_store_dwordx4 v[206:207], v[64:67], off sc1 nt
	s_nop 1
	v_pk_mul_f32 v[64:65], v[56:57], v[56:57]
	v_max_f32_e32 v58, 0, v58
	v_max_f32_e32 v56, 0, v62
	v_max_f32_e32 v57, 0, v63
	v_max_f32_e32 v60, 0, v60
	v_max_f32_e32 v61, 0, v61
	v_max_f32_e32 v59, 0, v59
	v_pk_mul_f32 v[62:63], v[56:57], v[56:57]
	v_pk_mul_f32 v[60:61], v[60:61], v[60:61]
	v_pk_mul_f32 v[66:67], v[58:59], v[58:59]
	v_cvt_pk_bf16_f32 v227, v62, v63
	v_cvt_pk_bf16_f32 v226, v60, v61
	v_cvt_pk_bf16_f32 v228, v64, v65
	v_cvt_pk_bf16_f32 v229, v66, v67
	v_max_f32_e32 v48, 0, v48
	v_max_f32_e32 v49, 0, v49
	v_pk_mul_f32 v[56:57], v[48:49], v[48:49]
	v_max_f32_e32 v50, 0, v50
	v_max_f32_e32 v52, 0, v52
	v_max_f32_e32 v53, 0, v53
	v_max_f32_e32 v48, 0, v54
	v_max_f32_e32 v49, 0, v55
	v_max_f32_e32 v51, 0, v51
	v_pk_mul_f32 v[52:53], v[52:53], v[52:53]
	v_pk_mul_f32 v[54:55], v[48:49], v[48:49]
	v_pk_mul_f32 v[58:59], v[50:51], v[50:51]
	v_cvt_pk_bf16_f32 v230, v52, v53
	v_cvt_pk_bf16_f32 v231, v54, v55
	v_cvt_pk_bf16_f32 v232, v56, v57
	v_cvt_pk_bf16_f32 v233, v58, v59
	v_max_f32_e32 v40, 0, v40
	v_max_f32_e32 v41, 0, v41
	v_pk_mul_f32 v[48:49], v[40:41], v[40:41]
	v_max_f32_e32 v42, 0, v42
	v_max_f32_e32 v40, 0, v46
	v_max_f32_e32 v41, 0, v47
	v_max_f32_e32 v44, 0, v44
	v_max_f32_e32 v45, 0, v45
	v_max_f32_e32 v43, 0, v43
	v_pk_mul_f32 v[46:47], v[40:41], v[40:41]
	v_pk_mul_f32 v[44:45], v[44:45], v[44:45]
	v_pk_mul_f32 v[50:51], v[42:43], v[42:43]
	v_cvt_pk_bf16_f32 v235, v46, v47
	v_cvt_pk_bf16_f32 v234, v44, v45
	v_cvt_pk_bf16_f32 v236, v48, v49
	v_cvt_pk_bf16_f32 v237, v50, v51
	v_max_f32_e32 v32, 0, v32
	v_max_f32_e32 v33, 0, v33
	v_pk_mul_f32 v[40:41], v[32:33], v[32:33]
	v_max_f32_e32 v34, 0, v34
	v_max_f32_e32 v36, 0, v36
	v_max_f32_e32 v37, 0, v37
	v_max_f32_e32 v32, 0, v38
	v_max_f32_e32 v33, 0, v39
	v_max_f32_e32 v35, 0, v35
	v_pk_mul_f32 v[36:37], v[36:37], v[36:37]
	v_pk_mul_f32 v[38:39], v[32:33], v[32:33]
	v_pk_mul_f32 v[42:43], v[34:35], v[34:35]
	v_cvt_pk_bf16_f32 v238, v36, v37
	v_cvt_pk_bf16_f32 v239, v38, v39
	v_cvt_pk_bf16_f32 v240, v40, v41
	v_cvt_pk_bf16_f32 v241, v42, v43
	v_max_f32_e32 v24, 0, v24
	v_max_f32_e32 v25, 0, v25
	v_pk_mul_f32 v[32:33], v[24:25], v[24:25]
	v_max_f32_e32 v26, 0, v26
	v_max_f32_e32 v24, 0, v30
	v_max_f32_e32 v25, 0, v31
	v_max_f32_e32 v28, 0, v28
	v_max_f32_e32 v29, 0, v29
	v_max_f32_e32 v27, 0, v27
	v_pk_mul_f32 v[30:31], v[24:25], v[24:25]
	v_pk_mul_f32 v[28:29], v[28:29], v[28:29]
	v_pk_mul_f32 v[34:35], v[26:27], v[26:27]
	v_cvt_pk_bf16_f32 v243, v30, v31
	v_cvt_pk_bf16_f32 v242, v28, v29
	v_cvt_pk_bf16_f32 v244, v32, v33
	v_cvt_pk_bf16_f32 v245, v34, v35
	v_max_f32_e32 v16, 0, v16
	v_max_f32_e32 v17, 0, v17
	v_pk_mul_f32 v[24:25], v[16:17], v[16:17]
	v_max_f32_e32 v18, 0, v18
	v_max_f32_e32 v20, 0, v20
	v_max_f32_e32 v21, 0, v21
	v_max_f32_e32 v16, 0, v22
	v_max_f32_e32 v17, 0, v23
	v_max_f32_e32 v19, 0, v19
	v_pk_mul_f32 v[20:21], v[20:21], v[20:21]
	v_pk_mul_f32 v[22:23], v[16:17], v[16:17]
	v_pk_mul_f32 v[26:27], v[18:19], v[18:19]
	v_cvt_pk_bf16_f32 v246, v20, v21
	v_cvt_pk_bf16_f32 v247, v22, v23
	v_cvt_pk_bf16_f32 v248, v24, v25
	v_cvt_pk_bf16_f32 v249, v26, v27
	v_max_f32_e32 v8, 0, v8
	v_max_f32_e32 v9, 0, v9
	v_pk_mul_f32 v[16:17], v[8:9], v[8:9]
	v_max_f32_e32 v10, 0, v10
	v_max_f32_e32 v8, 0, v14
	v_max_f32_e32 v9, 0, v15
	v_max_f32_e32 v12, 0, v12
	v_max_f32_e32 v13, 0, v13
	v_max_f32_e32 v11, 0, v11
	v_pk_mul_f32 v[14:15], v[8:9], v[8:9]
	v_pk_mul_f32 v[12:13], v[12:13], v[12:13]
	v_pk_mul_f32 v[18:19], v[10:11], v[10:11]
	v_cvt_pk_bf16_f32 v251, v14, v15
	v_cvt_pk_bf16_f32 v250, v12, v13
	v_cvt_pk_bf16_f32 v252, v16, v17
	v_cvt_pk_bf16_f32 v253, v18, v19
	v_max_f32_e32 v0, 0, v0
	v_max_f32_e32 v1, 0, v1
	v_pk_mul_f32 v[8:9], v[0:1], v[0:1]
	v_max_f32_e32 v2, 0, v2
	v_max_f32_e32 v4, 0, v4
	v_max_f32_e32 v5, 0, v5
	v_max_f32_e32 v0, 0, v6
	v_max_f32_e32 v1, 0, v7
	v_max_f32_e32 v3, 0, v3
	v_pk_mul_f32 v[4:5], v[4:5], v[4:5]
	v_pk_mul_f32 v[6:7], v[0:1], v[0:1]
	v_pk_mul_f32 v[10:11], v[2:3], v[2:3]
	v_cvt_pk_bf16_f32 v140, v4, v5
	v_cvt_pk_bf16_f32 v141, v6, v7
	v_cvt_pk_bf16_f32 v142, v8, v9
	v_cvt_pk_bf16_f32 v143, v10, v11
	s_andn2_b64 vcc, exec, s[4:5]
	s_mov_b64 s[4:5], -1
	s_mov_b32 s100, 1
	s_cbranch_vccnz .LBB0_869
	s_andn2_b64 vcc, exec, s[6:7]
	s_cbranch_vccnz .LBB0_868
	s_barrier
	s_branch .LBB0_868
.LBB0_883:
	global_store_dwordx4 v255, v[226:229], s[16:17] sc1 nt
	global_store_dwordx4 v255, v[230:233], s[18:19] sc1 nt
	global_store_dwordx4 v255, v[234:237], s[16:17] offset:1024 sc1 nt
	global_store_dwordx4 v255, v[238:241], s[18:19] offset:1024 sc1 nt
	global_store_dwordx4 v255, v[242:245], s[16:17] offset:2048 sc1 nt
	global_store_dwordx4 v255, v[246:249], s[18:19] offset:2048 sc1 nt
	global_store_dwordx4 v255, v[250:253], s[16:17] offset:3072 sc1 nt
	global_store_dwordx4 v255, v[140:143], s[18:19] offset:3072 sc1 nt
	s_waitcnt vmcnt(0)
	s_barrier
